# baseline (speedup 1.0000x reference)
; #define LDA(dst, b, h) for (int m = 0; m < 4; ++m) for (int k = 0; k < 2; ++k) \
;     dst[m][k] = *reinterpret_cast<const bf16x8*>((char*)SA(b, h) + lds_byte(wr * 64 + m * 16 + fr, k * 32 + fq * 8))
; #define LDB(dst, b, h) for (int n = 0; n < 2; ++n) for (int k = 0; k < 2; ++k) \
;     dst[n][k] = *reinterpret_cast<const bf16x8*>((char*)SB(b, h) + lds_byte(wc * 32 + n * 16 + fr, k * 32 + fq * 8))
; #define MMA(ai, bj, At, Bt_) do { __builtin_amdgcn_s_setprio(1); \
;     for (int m = 0; m < 4; ++m) for (int n = 0; n < 2; ++n) for (int k = 0; k < 2; ++k) \
;       acc[ai][bj][m][n] = __builtin_amdgcn_mfma_f32_16x16x32_bf16(Bt_[n][k], At[m][k], acc[ai][bj][m][n], 0, 0, 0); \
;     __builtin_amdgcn_s_setprio(0); } while (0)
; #define WAIT_V(n) asm volatile("s_waitcnt vmcnt(" #n ")" ::: "memory")
; #define WAIT_L(n) asm volatile("s_waitcnt lgkmcnt(" #n ")" ::: "memory")
; #define BAR __builtin_amdgcn_s_barrier()
; #define SCHED __builtin_amdgcn_sched_barrier(0)
; template <int EPI> ...
;     ...
;       LDB(B0, 0, 0); SCHED; LDA(At, 0, 0); STAGE(SA(1, 1), A, brow + HALF, t + 1);
;       WAIT_L(8); BAR; WAIT_L(0); MMA(0, 0, At, B0); BAR; SCHED;
;       LDB(B1, 0, 1); STAGE(SB(0, 0), Bt, bcol, t + 2);
;       BAR; WAIT_L(0); MMA(0, 1, At, B1); BAR;
;       LDA(At, 0, 1); STAGE(SA(0, 0), A, brow, t + 2);
;       BAR; WAIT_L(0); MMA(1, 0, At, B0); BAR; SCHED;
;       STAGE(SB(0, 1), Bt, bcol + HALF, t + 2);
;       WAIT_V(6); BAR; MMA(1, 1, At, B1); BAR;
.LBB0_541:
	s_add_u32 s29, s15, s16
	s_addc_u32 s30, s27, s17
	s_add_u32 s34, s29, 0x104000
	s_addc_u32 s35, s30, 0
	ds_read_b128 v[176:179], v168
	ds_read_b128 v[184:187], v169
	ds_read_b128 v[200:203], v170
	ds_read_b128 v[208:211], v171
	s_add_u32 m0, s32, 0xc000
	s_nop 0
	global_load_lds_dwordx4 v130, s[34:35]
	s_add_u32 m0, s32, 0xe000
	s_nop 0
	global_load_lds_dwordx4 v132, s[34:35]
	s_waitcnt lgkmcnt(4)
	s_barrier
	s_waitcnt lgkmcnt(0)
	s_setprio 1
	s_waitcnt lgkmcnt(0)
	v_mfma_f32_16x16x32_bf16 v[126:129], v[144:147], v[176:179], v[126:129]
	ds_read_b128 v[180:183], v168 offset:1024
	v_mfma_f32_16x16x32_bf16 v[122:125], v[152:155], v[176:179], v[122:125]
	ds_read_b128 v[188:191], v169 offset:1024
	v_mfma_f32_16x16x32_bf16 v[118:121], v[144:147], v[184:187], v[118:121]
	ds_read_b128 v[204:207], v170 offset:1024
	v_mfma_f32_16x16x32_bf16 v[114:117], v[152:155], v[184:187], v[114:117]
	ds_read_b128 v[212:215], v171 offset:1024
	v_mfma_f32_16x16x32_bf16 v[110:113], v[144:147], v[200:203], v[110:113]
	v_mfma_f32_16x16x32_bf16 v[106:109], v[152:155], v[200:203], v[106:109]
	v_mfma_f32_16x16x32_bf16 v[102:105], v[144:147], v[208:211], v[102:105]
	v_mfma_f32_16x16x32_bf16 v[98:101], v[152:155], v[208:211], v[98:101]
	s_waitcnt lgkmcnt(0)
	v_mfma_f32_16x16x32_bf16 v[126:129], v[148:151], v[180:183], v[126:129]
	v_mfma_f32_16x16x32_bf16 v[122:125], v[156:159], v[180:183], v[122:125]
	v_mfma_f32_16x16x32_bf16 v[118:121], v[148:151], v[188:191], v[118:121]
	v_mfma_f32_16x16x32_bf16 v[114:117], v[156:159], v[188:191], v[114:117]
	v_mfma_f32_16x16x32_bf16 v[110:113], v[148:151], v[204:207], v[110:113]
	v_mfma_f32_16x16x32_bf16 v[106:109], v[156:159], v[204:207], v[106:109]
	v_mfma_f32_16x16x32_bf16 v[102:105], v[148:151], v[212:215], v[102:105]
	v_mfma_f32_16x16x32_bf16 v[98:101], v[156:159], v[212:215], v[98:101]
	s_setprio 0
	s_barrier
	s_add_u32 s31, s25, s16
	s_addc_u32 s34, s26, s17
	s_add_u32 s36, s31, 0x8000
	s_addc_u32 s37, s34, 0
	ds_read_b128 v[216:219], v172
	ds_read_b128 v[220:223], v172 offset:1024
	ds_read_b128 v[224:227], v172 offset:2048
	ds_read_b128 v[228:231], v172 offset:3072
	s_add_u32 m0, s32, 0x10000
	s_nop 0
	global_load_lds_dwordx4 v130, s[36:37]
	s_add_u32 m0, s32, 0x12000
	s_nop 0
	global_load_lds_dwordx4 v132, s[36:37]
	s_barrier
	s_waitcnt lgkmcnt(0)
	s_setprio 1
	s_waitcnt lgkmcnt(0)
	v_mfma_f32_16x16x32_bf16 v[94:97], v[216:219], v[176:179], v[94:97]
	v_mfma_f32_16x16x32_bf16 v[90:93], v[224:227], v[176:179], v[90:93]
	v_mfma_f32_16x16x32_bf16 v[86:89], v[216:219], v[184:187], v[86:89]
	v_mfma_f32_16x16x32_bf16 v[82:85], v[224:227], v[184:187], v[82:85]
	v_mfma_f32_16x16x32_bf16 v[78:81], v[216:219], v[200:203], v[78:81]
	v_mfma_f32_16x16x32_bf16 v[74:77], v[224:227], v[200:203], v[74:77]
	v_mfma_f32_16x16x32_bf16 v[70:73], v[216:219], v[208:211], v[70:73]
	v_mfma_f32_16x16x32_bf16 v[66:69], v[224:227], v[208:211], v[66:69]
	v_mfma_f32_16x16x32_bf16 v[94:97], v[220:223], v[180:183], v[94:97]
	v_mfma_f32_16x16x32_bf16 v[90:93], v[228:231], v[180:183], v[90:93]
	v_mfma_f32_16x16x32_bf16 v[86:89], v[220:223], v[188:191], v[86:89]
	v_mfma_f32_16x16x32_bf16 v[82:85], v[228:231], v[188:191], v[82:85]
	v_mfma_f32_16x16x32_bf16 v[78:81], v[220:223], v[204:207], v[78:81]
	v_mfma_f32_16x16x32_bf16 v[74:77], v[228:231], v[204:207], v[74:77]
	v_mfma_f32_16x16x32_bf16 v[70:73], v[220:223], v[212:215], v[70:73]
	v_mfma_f32_16x16x32_bf16 v[66:69], v[228:231], v[212:215], v[66:69]
	s_setprio 0
	s_add_u32 s36, s29, 0x8000
	s_addc_u32 s37, s30, 0
	s_barrier
	ds_read_b128 v[176:179], v168 offset:16384
	ds_read_b128 v[184:187], v169 offset:16384
	ds_read_b128 v[200:203], v170 offset:16384
	ds_read_b128 v[208:211], v171 offset:16384
	s_add_u32 m0, s32, 0x0
	s_nop 0
	global_load_lds_dwordx4 v130, s[36:37]
	s_add_u32 m0, s32, 0x2000
	s_nop 0
	global_load_lds_dwordx4 v132, s[36:37]
	s_waitcnt vmcnt(10)
	s_barrier
	s_waitcnt lgkmcnt(0)
	s_setprio 1
	s_waitcnt lgkmcnt(0)
	v_mfma_f32_16x16x32_bf16 v[62:65], v[144:147], v[176:179], v[62:65]
	ds_read_b128 v[180:183], v168 offset:17408
	v_mfma_f32_16x16x32_bf16 v[58:61], v[152:155], v[176:179], v[58:61]
	ds_read_b128 v[188:191], v169 offset:17408
	v_mfma_f32_16x16x32_bf16 v[54:57], v[144:147], v[184:187], v[54:57]
	ds_read_b128 v[204:207], v170 offset:17408
	v_mfma_f32_16x16x32_bf16 v[50:53], v[152:155], v[184:187], v[50:53]
	ds_read_b128 v[212:215], v171 offset:17408
	v_mfma_f32_16x16x32_bf16 v[46:49], v[144:147], v[200:203], v[46:49]
	v_mfma_f32_16x16x32_bf16 v[42:45], v[152:155], v[200:203], v[42:45]
	v_mfma_f32_16x16x32_bf16 v[38:41], v[144:147], v[208:211], v[38:41]
	v_mfma_f32_16x16x32_bf16 v[34:37], v[152:155], v[208:211], v[34:37]
	s_waitcnt lgkmcnt(0)
	v_mfma_f32_16x16x32_bf16 v[62:65], v[148:151], v[180:183], v[62:65]
	v_mfma_f32_16x16x32_bf16 v[58:61], v[156:159], v[180:183], v[58:61]
	v_mfma_f32_16x16x32_bf16 v[54:57], v[148:151], v[188:191], v[54:57]
	v_mfma_f32_16x16x32_bf16 v[50:53], v[156:159], v[188:191], v[50:53]
	v_mfma_f32_16x16x32_bf16 v[46:49], v[148:151], v[204:207], v[46:49]
	v_mfma_f32_16x16x32_bf16 v[42:45], v[156:159], v[204:207], v[42:45]
	v_mfma_f32_16x16x32_bf16 v[38:41], v[148:151], v[212:215], v[38:41]
	v_mfma_f32_16x16x32_bf16 v[34:37], v[156:159], v[212:215], v[34:37]
	s_setprio 0
	s_barrier
	ds_read_b128 v[144:147], v173
	ds_read_b128 v[148:151], v173 offset:1024
	ds_read_b128 v[152:155], v173 offset:2048
	ds_read_b128 v[156:159], v173 offset:3072
	s_add_u32 s36, s31, 0x108000
	s_addc_u32 s37, s34, 0
	s_add_u32 m0, s32, 0x14000
	s_nop 0
	global_load_lds_dwordx4 v130, s[36:37]
	s_add_u32 m0, s32, 0x16000
	s_nop 0
	global_load_lds_dwordx4 v132, s[36:37]
	s_waitcnt vmcnt(6)
	s_barrier
; #define LDA(dst, b, h) for (int m = 0; m < 4; ++m) for (int k = 0; k < 2; ++k) \
;     dst[m][k] = *reinterpret_cast<const bf16x8*>((char*)SA(b, h) + lds_byte(wr * 64 + m * 16 + fr, k * 32 + fq * 8))
; #define LDB(dst, b, h) for (int n = 0; n < 2; ++n) for (int k = 0; k < 2; ++k) \
;     dst[n][k] = *reinterpret_cast<const bf16x8*>((char*)SB(b, h) + lds_byte(wc * 32 + n * 16 + fr, k * 32 + fq * 8))
; #define MMA(ai, bj, At, Bt_) do { __builtin_amdgcn_s_setprio(1); \
;     for (int m = 0; m < 4; ++m) for (int n = 0; n < 2; ++n) for (int k = 0; k < 2; ++k) \
;       acc[ai][bj][m][n] = __builtin_amdgcn_mfma_f32_16x16x32_bf16(Bt_[n][k], At[m][k], acc[ai][bj][m][n], 0, 0, 0); \
;     __builtin_amdgcn_s_setprio(0); } while (0)
; #define WAIT_V(n) asm volatile("s_waitcnt vmcnt(" #n ")" ::: "memory")
; #define WAIT_L(n) asm volatile("s_waitcnt lgkmcnt(" #n ")" ::: "memory")
; #define BAR __builtin_amdgcn_s_barrier()
; #define SCHED __builtin_amdgcn_sched_barrier(0)
; template <int EPI> ...
;     ...
;       LDB(B0, 1, 0); SCHED; LDA(At, 1, 0); STAGE(SA(0, 1), A, brow + HALF, t + 2);
;       WAIT_L(8); BAR; WAIT_L(0); MMA(0, 0, At, B0); BAR; SCHED;
;       LDB(B1, 1, 1); STAGE(SB(1, 0), Bt, bcol, t + 3);
;       BAR; WAIT_L(0); MMA(0, 1, At, B1); BAR;
;       LDA(At, 1, 1); STAGE(SA(1, 0), A, brow, t + 3);
;       BAR; WAIT_L(0); MMA(1, 0, At, B0); BAR; SCHED;
;       STAGE(SB(1, 1), Bt, bcol + HALF, t + 3);
;       WAIT_V(6); BAR; MMA(1, 1, At, B1); BAR;
	s_setprio 1
	v_mfma_f32_16x16x32_bf16 v[30:33], v[216:219], v[176:179], v[30:33]
	v_mfma_f32_16x16x32_bf16 v[26:29], v[224:227], v[176:179], v[26:29]
	v_mfma_f32_16x16x32_bf16 v[22:25], v[216:219], v[184:187], v[22:25]
	v_mfma_f32_16x16x32_bf16 v[18:21], v[224:227], v[184:187], v[18:21]
	v_mfma_f32_16x16x32_bf16 v[14:17], v[216:219], v[200:203], v[14:17]
	v_mfma_f32_16x16x32_bf16 v[10:13], v[224:227], v[200:203], v[10:13]
	v_mfma_f32_16x16x32_bf16 v[6:9], v[216:219], v[208:211], v[6:9]
	v_mfma_f32_16x16x32_bf16 v[2:5], v[224:227], v[208:211], v[2:5]
	v_mfma_f32_16x16x32_bf16 v[30:33], v[220:223], v[180:183], v[30:33]
	v_mfma_f32_16x16x32_bf16 v[26:29], v[228:231], v[180:183], v[26:29]
	v_mfma_f32_16x16x32_bf16 v[22:25], v[220:223], v[188:191], v[22:25]
	v_mfma_f32_16x16x32_bf16 v[18:21], v[228:231], v[188:191], v[18:21]
	v_mfma_f32_16x16x32_bf16 v[14:17], v[220:223], v[204:207], v[14:17]
	v_mfma_f32_16x16x32_bf16 v[10:13], v[228:231], v[204:207], v[10:13]
	v_mfma_f32_16x16x32_bf16 v[6:9], v[220:223], v[212:215], v[6:9]
	v_mfma_f32_16x16x32_bf16 v[2:5], v[228:231], v[212:215], v[2:5]
	s_setprio 0
	s_barrier
	s_add_u32 s36, s29, 0x108000
	s_addc_u32 s37, s30, 0
	ds_read_b128 v[176:179], v168 offset:32768
	ds_read_b128 v[184:187], v169 offset:32768
	ds_read_b128 v[200:203], v170 offset:32768
	ds_read_b128 v[208:211], v171 offset:32768
	s_add_u32 m0, s32, 0x4000
	s_nop 0
	global_load_lds_dwordx4 v130, s[36:37]
	s_add_u32 m0, s32, 0x6000
	s_nop 0
	global_load_lds_dwordx4 v132, s[36:37]
	s_waitcnt lgkmcnt(4)
	s_barrier
	s_waitcnt lgkmcnt(0)
	s_setprio 1
	s_waitcnt lgkmcnt(0)
	v_mfma_f32_16x16x32_bf16 v[126:129], v[144:147], v[176:179], v[126:129]
	ds_read_b128 v[180:183], v168 offset:33792
	v_mfma_f32_16x16x32_bf16 v[122:125], v[152:155], v[176:179], v[122:125]
	ds_read_b128 v[188:191], v169 offset:33792
	v_mfma_f32_16x16x32_bf16 v[118:121], v[144:147], v[184:187], v[118:121]
	ds_read_b128 v[204:207], v170 offset:33792
	v_mfma_f32_16x16x32_bf16 v[114:117], v[152:155], v[184:187], v[114:117]
	ds_read_b128 v[212:215], v171 offset:33792
	v_mfma_f32_16x16x32_bf16 v[110:113], v[144:147], v[200:203], v[110:113]
	v_mfma_f32_16x16x32_bf16 v[106:109], v[152:155], v[200:203], v[106:109]
	v_mfma_f32_16x16x32_bf16 v[102:105], v[144:147], v[208:211], v[102:105]
	v_mfma_f32_16x16x32_bf16 v[98:101], v[152:155], v[208:211], v[98:101]
	s_waitcnt lgkmcnt(0)
	v_mfma_f32_16x16x32_bf16 v[126:129], v[148:151], v[180:183], v[126:129]
	v_mfma_f32_16x16x32_bf16 v[122:125], v[156:159], v[180:183], v[122:125]
	v_mfma_f32_16x16x32_bf16 v[118:121], v[148:151], v[188:191], v[118:121]
	v_mfma_f32_16x16x32_bf16 v[114:117], v[156:159], v[188:191], v[114:117]
	v_mfma_f32_16x16x32_bf16 v[110:113], v[148:151], v[204:207], v[110:113]
	v_mfma_f32_16x16x32_bf16 v[106:109], v[156:159], v[204:207], v[106:109]
	v_mfma_f32_16x16x32_bf16 v[102:105], v[148:151], v[212:215], v[102:105]
	v_mfma_f32_16x16x32_bf16 v[98:101], v[156:159], v[212:215], v[98:101]
	s_setprio 0
	s_barrier
	s_add_u32 s36, s31, 0xc000
	s_addc_u32 s37, s34, 0
	ds_read_b128 v[216:219], v174
	ds_read_b128 v[220:223], v174 offset:1024
	ds_read_b128 v[224:227], v174 offset:2048
	ds_read_b128 v[228:231], v174 offset:3072
	s_add_u32 m0, s32, 0x18000
	s_nop 0
	global_load_lds_dwordx4 v130, s[36:37]
	s_add_u32 m0, s32, 0x1a000
	s_nop 0
	global_load_lds_dwordx4 v132, s[36:37]
	s_barrier
	s_waitcnt lgkmcnt(0)
	s_setprio 1
	s_waitcnt lgkmcnt(0)
	v_mfma_f32_16x16x32_bf16 v[94:97], v[216:219], v[176:179], v[94:97]
	v_mfma_f32_16x16x32_bf16 v[90:93], v[224:227], v[176:179], v[90:93]
	v_mfma_f32_16x16x32_bf16 v[86:89], v[216:219], v[184:187], v[86:89]
	v_mfma_f32_16x16x32_bf16 v[82:85], v[224:227], v[184:187], v[82:85]
	v_mfma_f32_16x16x32_bf16 v[78:81], v[216:219], v[200:203], v[78:81]
	v_mfma_f32_16x16x32_bf16 v[74:77], v[224:227], v[200:203], v[74:77]
	v_mfma_f32_16x16x32_bf16 v[70:73], v[216:219], v[208:211], v[70:73]
	v_mfma_f32_16x16x32_bf16 v[66:69], v[224:227], v[208:211], v[66:69]
	v_mfma_f32_16x16x32_bf16 v[94:97], v[220:223], v[180:183], v[94:97]
	v_mfma_f32_16x16x32_bf16 v[90:93], v[228:231], v[180:183], v[90:93]
	v_mfma_f32_16x16x32_bf16 v[86:89], v[220:223], v[188:191], v[86:89]
	v_mfma_f32_16x16x32_bf16 v[82:85], v[228:231], v[188:191], v[82:85]
	v_mfma_f32_16x16x32_bf16 v[78:81], v[220:223], v[204:207], v[78:81]
	v_mfma_f32_16x16x32_bf16 v[74:77], v[228:231], v[204:207], v[74:77]
	v_mfma_f32_16x16x32_bf16 v[70:73], v[220:223], v[212:215], v[70:73]
	v_mfma_f32_16x16x32_bf16 v[66:69], v[228:231], v[212:215], v[66:69]
	s_setprio 0
	s_add_u32 s36, s29, 0xc000
	s_addc_u32 s37, s30, 0
	s_barrier
	ds_read_b128 v[176:179], v168 offset:49152
	ds_read_b128 v[184:187], v169 offset:49152
	ds_read_b128 v[200:203], v170 offset:49152
	ds_read_b128 v[208:211], v171 offset:49152
	s_add_u32 m0, s32, 0x8000
	s_nop 0
	global_load_lds_dwordx4 v130, s[36:37]
	s_add_u32 m0, s32, 0xa000
	s_nop 0
	global_load_lds_dwordx4 v132, s[36:37]
	s_waitcnt vmcnt(10)
	s_barrier
; #define LDA(dst, b, h) for (int m = 0; m < 4; ++m) for (int k = 0; k < 2; ++k) \
;     dst[m][k] = *reinterpret_cast<const bf16x8*>((char*)SA(b, h) + lds_byte(wr * 64 + m * 16 + fr, k * 32 + fq * 8))
; #define LDB(dst, b, h) for (int n = 0; n < 2; ++n) for (int k = 0; k < 2; ++k) \
;     dst[n][k] = *reinterpret_cast<const bf16x8*>((char*)SB(b, h) + lds_byte(wc * 32 + n * 16 + fr, k * 32 + fq * 8))
; #define MMA(ai, bj, At, Bt_) do { __builtin_amdgcn_s_setprio(1); \
;     for (int m = 0; m < 4; ++m) for (int n = 0; n < 2; ++n) for (int k = 0; k < 2; ++k) \
;       acc[ai][bj][m][n] = __builtin_amdgcn_mfma_f32_16x16x32_bf16(Bt_[n][k], At[m][k], acc[ai][bj][m][n], 0, 0, 0); \
;     __builtin_amdgcn_s_setprio(0); } while (0)
; #define WAIT_V(n) asm volatile("s_waitcnt vmcnt(" #n ")" ::: "memory")
; #define WAIT_L(n) asm volatile("s_waitcnt lgkmcnt(" #n ")" ::: "memory")
; #define BAR __builtin_amdgcn_s_barrier()
; #define SCHED __builtin_amdgcn_sched_barrier(0)
; template <int EPI> ...
;     ...
;       LDB(B0, 1, 0); SCHED; LDA(At, 1, 0); STAGE(SA(0, 1), A, brow + HALF, t + 2);
;       WAIT_L(8); BAR; WAIT_L(0); MMA(0, 0, At, B0); BAR; SCHED;
;       LDB(B1, 1, 1); STAGE(SB(1, 0), Bt, bcol, t + 3);
;       BAR; WAIT_L(0); MMA(0, 1, At, B1); BAR;
;       LDA(At, 1, 1); STAGE(SA(1, 0), A, brow, t + 3);
;       BAR; WAIT_L(0); MMA(1, 0, At, B0); BAR; SCHED;
;       STAGE(SB(1, 1), Bt, bcol + HALF, t + 3);
;       WAIT_V(6); BAR; MMA(1, 1, At, B1); BAR;
;     }
;     { LDB(B0, 0, 0); LDA(At, 0, 0); STAGE(SA(1, 1), A, brow + HALF, nt - 1);
;       BAR; WAIT_L(0); MMA(0, 0, At, B0); BAR;
;       LDB(B1, 0, 1); BAR; WAIT_L(0); MMA(0, 1, At, B1); BAR;
;       LDA(At, 0, 1); WAIT_V(4); BAR; WAIT_L(0); MMA(1, 0, At, B0); MMA(1, 1, At, B1); BAR; }
	s_waitcnt lgkmcnt(0)
	s_setprio 1
	s_waitcnt lgkmcnt(0)
	v_mfma_f32_16x16x32_bf16 v[62:65], v[144:147], v[176:179], v[62:65]
	ds_read_b128 v[180:183], v168 offset:50176
	v_mfma_f32_16x16x32_bf16 v[58:61], v[152:155], v[176:179], v[58:61]
	ds_read_b128 v[188:191], v169 offset:50176
	v_mfma_f32_16x16x32_bf16 v[54:57], v[144:147], v[184:187], v[54:57]
	ds_read_b128 v[204:207], v170 offset:50176
	v_mfma_f32_16x16x32_bf16 v[50:53], v[152:155], v[184:187], v[50:53]
	ds_read_b128 v[212:215], v171 offset:50176
	v_mfma_f32_16x16x32_bf16 v[46:49], v[144:147], v[200:203], v[46:49]
	v_mfma_f32_16x16x32_bf16 v[42:45], v[152:155], v[200:203], v[42:45]
	v_mfma_f32_16x16x32_bf16 v[38:41], v[144:147], v[208:211], v[38:41]
	v_mfma_f32_16x16x32_bf16 v[34:37], v[152:155], v[208:211], v[34:37]
	s_waitcnt lgkmcnt(0)
	v_mfma_f32_16x16x32_bf16 v[62:65], v[148:151], v[180:183], v[62:65]
	v_mfma_f32_16x16x32_bf16 v[58:61], v[156:159], v[180:183], v[58:61]
	v_mfma_f32_16x16x32_bf16 v[54:57], v[148:151], v[188:191], v[54:57]
	v_mfma_f32_16x16x32_bf16 v[50:53], v[156:159], v[188:191], v[50:53]
	v_mfma_f32_16x16x32_bf16 v[46:49], v[148:151], v[204:207], v[46:49]
	v_mfma_f32_16x16x32_bf16 v[42:45], v[156:159], v[204:207], v[42:45]
	v_mfma_f32_16x16x32_bf16 v[38:41], v[148:151], v[212:215], v[38:41]
	v_mfma_f32_16x16x32_bf16 v[34:37], v[156:159], v[212:215], v[34:37]
	s_setprio 0
	s_barrier
	ds_read_b128 v[144:147], v167
	ds_read_b128 v[148:151], v167 offset:1024
	ds_read_b128 v[152:155], v167 offset:2048
	ds_read_b128 v[156:159], v167 offset:3072
	s_add_u32 s30, s31, 0x10c000
	s_addc_u32 s31, s34, 0
	s_add_u32 m0, s32, 0x1c000
	s_nop 0
	global_load_lds_dwordx4 v130, s[30:31]
	s_add_u32 m0, s32, 0x1e000
	s_nop 0
	global_load_lds_dwordx4 v132, s[30:31]
	s_waitcnt vmcnt(6)
	s_barrier
	s_setprio 1
	v_mfma_f32_16x16x32_bf16 v[30:33], v[216:219], v[176:179], v[30:33]
	v_mfma_f32_16x16x32_bf16 v[26:29], v[224:227], v[176:179], v[26:29]
	v_mfma_f32_16x16x32_bf16 v[22:25], v[216:219], v[184:187], v[22:25]
	v_mfma_f32_16x16x32_bf16 v[18:21], v[224:227], v[184:187], v[18:21]
	v_mfma_f32_16x16x32_bf16 v[14:17], v[216:219], v[200:203], v[14:17]
	v_mfma_f32_16x16x32_bf16 v[10:13], v[224:227], v[200:203], v[10:13]
	v_mfma_f32_16x16x32_bf16 v[6:9], v[216:219], v[208:211], v[6:9]
	v_mfma_f32_16x16x32_bf16 v[2:5], v[224:227], v[208:211], v[2:5]
	v_mfma_f32_16x16x32_bf16 v[30:33], v[220:223], v[180:183], v[30:33]
	v_mfma_f32_16x16x32_bf16 v[26:29], v[228:231], v[180:183], v[26:29]
	v_mfma_f32_16x16x32_bf16 v[22:25], v[220:223], v[188:191], v[22:25]
	v_mfma_f32_16x16x32_bf16 v[18:21], v[228:231], v[188:191], v[18:21]
	v_mfma_f32_16x16x32_bf16 v[14:17], v[220:223], v[204:207], v[14:17]
	v_mfma_f32_16x16x32_bf16 v[10:13], v[228:231], v[204:207], v[10:13]
	v_mfma_f32_16x16x32_bf16 v[6:9], v[220:223], v[212:215], v[6:9]
	v_mfma_f32_16x16x32_bf16 v[2:5], v[228:231], v[212:215], v[2:5]
	s_setprio 0
	s_add_i32 s28, s28, 2
	s_add_u32 s16, s16, 0x8000
	s_addc_u32 s17, s17, 0
	s_cmp_lt_u32 s28, 60
	s_barrier
	s_cbranch_scc1 .LBB0_541
	s_or_b32 s14, s14, 1
	s_ashr_i32 s15, s14, 31
	s_lshl_b64 s[14:15], s[14:15], 20
	s_add_u32 s14, s10, s14
	s_addc_u32 s15, s11, s15
	s_add_u32 s14, s14, 0xfc000
	s_addc_u32 s15, s15, 0
	v_readfirstlane_b32 s16, v141
	ds_read_b128 v[134:137], v167
	ds_read_b128 v[144:147], v167 offset:1024
	ds_read_b128 v[148:151], v167 offset:2048
	ds_read_b128 v[152:155], v167 offset:3072
	ds_read_b128 v[156:159], v168
	ds_read_b128 v[176:179], v168 offset:1024
	ds_read_b128 v[180:183], v169
	ds_read_b128 v[184:187], v169 offset:1024
	ds_read_b128 v[188:191], v170
	ds_read_b128 v[200:203], v170 offset:1024
	ds_read_b128 v[204:207], v171
	ds_read_b128 v[208:211], v171 offset:1024
	s_mov_b32 m0, s16
	v_lshl_add_u64 v[212:213], s[14:15], 0, v[130:131]
	global_load_lds_dwordx4 v[212:213], off
	v_lshl_add_u64 v[212:213], s[14:15], 0, v[132:133]
	v_readfirstlane_b32 s14, v142
	s_mov_b32 m0, s14
	s_nop 0
	global_load_lds_dwordx4 v[212:213], off
	s_barrier
	s_waitcnt lgkmcnt(0)
	s_setprio 1
	s_waitcnt lgkmcnt(0)
	v_mfma_f32_16x16x32_bf16 v[126:129], v[134:137], v[156:159], v[126:129]
	v_mfma_f32_16x16x32_bf16 v[122:125], v[148:151], v[156:159], v[122:125]
	v_mfma_f32_16x16x32_bf16 v[118:121], v[134:137], v[180:183], v[118:121]
	v_mfma_f32_16x16x32_bf16 v[114:117], v[148:151], v[180:183], v[114:117]
	v_mfma_f32_16x16x32_bf16 v[102:105], v[134:137], v[204:207], v[102:105]
	v_mfma_f32_16x16x32_bf16 v[98:101], v[148:151], v[204:207], v[98:101]
	v_mfma_f32_16x16x32_bf16 v[126:129], v[144:147], v[176:179], v[126:129]
	v_mfma_f32_16x16x32_bf16 v[122:125], v[152:155], v[176:179], v[122:125]
	v_mfma_f32_16x16x32_bf16 v[118:121], v[144:147], v[184:187], v[118:121]
	v_mfma_f32_16x16x32_bf16 v[114:117], v[152:155], v[184:187], v[114:117]
	v_mfma_f32_16x16x32_bf16 v[110:113], v[134:137], v[188:191], v[110:113]
	v_mfma_f32_16x16x32_bf16 v[106:109], v[148:151], v[188:191], v[106:109]
	v_mfma_f32_16x16x32_bf16 v[102:105], v[144:147], v[208:211], v[102:105]
	v_mfma_f32_16x16x32_bf16 v[98:101], v[152:155], v[208:211], v[98:101]
	v_mfma_f32_16x16x32_bf16 v[212:215], v[144:147], v[200:203], v[110:113]
	v_mfma_f32_16x16x32_bf16 v[216:219], v[152:155], v[200:203], v[106:109]
	s_setprio 0
	s_barrier
	s_nop 1
	ds_read_b128 v[106:109], v172
	ds_read_b128 v[110:113], v172 offset:1024
	ds_read_b128 v[220:223], v172 offset:2048
	ds_read_b128 v[224:227], v172 offset:3072
	s_barrier
; #define LDA(dst, b, h) for (int m = 0; m < 4; ++m) for (int k = 0; k < 2; ++k) \
;     dst[m][k] = *reinterpret_cast<const bf16x8*>((char*)SA(b, h) + lds_byte(wr * 64 + m * 16 + fr, k * 32 + fq * 8))
; #define LDB(dst, b, h) for (int n = 0; n < 2; ++n) for (int k = 0; k < 2; ++k) \
;     dst[n][k] = *reinterpret_cast<const bf16x8*>((char*)SB(b, h) + lds_byte(wc * 32 + n * 16 + fr, k * 32 + fq * 8))
; #define MMA(ai, bj, At, Bt_) do { __builtin_amdgcn_s_setprio(1); \
;     for (int m = 0; m < 4; ++m) for (int n = 0; n < 2; ++n) for (int k = 0; k < 2; ++k) \
;       acc[ai][bj][m][n] = __builtin_amdgcn_mfma_f32_16x16x32_bf16(Bt_[n][k], At[m][k], acc[ai][bj][m][n], 0, 0, 0); \
;     __builtin_amdgcn_s_setprio(0); } while (0)
; #define WAIT_V(n) asm volatile("s_waitcnt vmcnt(" #n ")" ::: "memory")
; #define WAIT_L(n) asm volatile("s_waitcnt lgkmcnt(" #n ")" ::: "memory")
; #define BAR __builtin_amdgcn_s_barrier()
; template <int EPI> ...
;     ...
;       BAR; WAIT_L(0); MMA(0, 0, At, B0); BAR;
;       LDB(B1, 0, 1); BAR; WAIT_L(0); MMA(0, 1, At, B1); BAR;
;       LDA(At, 0, 1); WAIT_V(4); BAR; WAIT_L(0); MMA(1, 0, At, B0); MMA(1, 1, At, B1); BAR; }
;     { LDB(B0, 1, 0); LDA(At, 1, 0); WAIT_V(2); BAR; WAIT_L(0); MMA(0, 0, At, B0); BAR;
	s_waitcnt lgkmcnt(0)
	s_setprio 1
	s_waitcnt lgkmcnt(0)
	v_mfma_f32_16x16x32_bf16 v[86:89], v[106:109], v[180:183], v[86:89]
	v_mfma_f32_16x16x32_bf16 v[82:85], v[220:223], v[180:183], v[82:85]
	v_mfma_f32_16x16x32_bf16 v[70:73], v[106:109], v[204:207], v[70:73]
	v_mfma_f32_16x16x32_bf16 v[66:69], v[220:223], v[204:207], v[66:69]
	v_mfma_f32_16x16x32_bf16 v[94:97], v[106:109], v[156:159], v[94:97]
	v_mfma_f32_16x16x32_bf16 v[90:93], v[220:223], v[156:159], v[90:93]
	v_mfma_f32_16x16x32_bf16 v[86:89], v[110:113], v[184:187], v[86:89]
	v_mfma_f32_16x16x32_bf16 v[82:85], v[224:227], v[184:187], v[82:85]
	v_mfma_f32_16x16x32_bf16 v[78:81], v[106:109], v[188:191], v[78:81]
	v_mfma_f32_16x16x32_bf16 v[74:77], v[220:223], v[188:191], v[74:77]
	v_mfma_f32_16x16x32_bf16 v[70:73], v[110:113], v[208:211], v[70:73]
	v_mfma_f32_16x16x32_bf16 v[66:69], v[224:227], v[208:211], v[66:69]
	v_mfma_f32_16x16x32_bf16 v[228:231], v[110:113], v[176:179], v[94:97]
	v_mfma_f32_16x16x32_bf16 v[156:159], v[224:227], v[176:179], v[90:93]
	v_mfma_f32_16x16x32_bf16 v[176:179], v[110:113], v[200:203], v[78:81]
	v_mfma_f32_16x16x32_bf16 v[180:183], v[224:227], v[200:203], v[74:77]
	s_setprio 0
	s_barrier
	s_nop 0
	ds_read_b128 v[74:77], v168 offset:16384
	ds_read_b128 v[78:81], v168 offset:17408
	ds_read_b128 v[90:93], v169 offset:16384
	ds_read_b128 v[94:97], v169 offset:17408
	ds_read_b128 v[184:187], v170 offset:16384
	ds_read_b128 v[188:191], v170 offset:17408
	ds_read_b128 v[200:203], v171 offset:16384
	ds_read_b128 v[204:207], v171 offset:17408
	s_waitcnt vmcnt(4)
	s_barrier
	s_waitcnt lgkmcnt(0)
	s_setprio 1
	s_waitcnt lgkmcnt(0)
	v_mfma_f32_16x16x32_bf16 v[62:65], v[134:137], v[74:77], v[62:65]
	v_mfma_f32_16x16x32_bf16 v[58:61], v[148:151], v[74:77], v[58:61]
	v_mfma_f32_16x16x32_bf16 v[54:57], v[134:137], v[90:93], v[54:57]
	v_mfma_f32_16x16x32_bf16 v[50:53], v[148:151], v[90:93], v[50:53]
	v_mfma_f32_16x16x32_bf16 v[38:41], v[134:137], v[200:203], v[38:41]
	v_mfma_f32_16x16x32_bf16 v[34:37], v[148:151], v[200:203], v[34:37]
	v_mfma_f32_16x16x32_bf16 v[62:65], v[144:147], v[78:81], v[62:65]
	v_mfma_f32_16x16x32_bf16 v[58:61], v[152:155], v[78:81], v[58:61]
	v_mfma_f32_16x16x32_bf16 v[54:57], v[144:147], v[94:97], v[54:57]
	v_mfma_f32_16x16x32_bf16 v[50:53], v[152:155], v[94:97], v[50:53]
	v_mfma_f32_16x16x32_bf16 v[46:49], v[134:137], v[184:187], v[46:49]
	v_mfma_f32_16x16x32_bf16 v[42:45], v[148:151], v[184:187], v[42:45]
	v_mfma_f32_16x16x32_bf16 v[38:41], v[144:147], v[204:207], v[38:41]
	v_mfma_f32_16x16x32_bf16 v[34:37], v[152:155], v[204:207], v[34:37]
	v_mfma_f32_16x16x32_bf16 v[208:211], v[144:147], v[188:191], v[46:49]
	v_mfma_f32_16x16x32_bf16 v[232:235], v[152:155], v[188:191], v[42:45]
	s_setprio 0
	s_setprio 1
	v_mfma_f32_16x16x32_bf16 v[22:25], v[106:109], v[90:93], v[22:25]
	v_mfma_f32_16x16x32_bf16 v[18:21], v[220:223], v[90:93], v[18:21]
	v_mfma_f32_16x16x32_bf16 v[6:9], v[106:109], v[200:203], v[6:9]
	v_mfma_f32_16x16x32_bf16 v[2:5], v[220:223], v[200:203], v[2:5]
	v_mfma_f32_16x16x32_bf16 v[30:33], v[106:109], v[74:77], v[30:33]
	v_mfma_f32_16x16x32_bf16 v[26:29], v[220:223], v[74:77], v[26:29]
	v_mfma_f32_16x16x32_bf16 v[22:25], v[110:113], v[94:97], v[22:25]
	v_mfma_f32_16x16x32_bf16 v[18:21], v[224:227], v[94:97], v[18:21]
	v_mfma_f32_16x16x32_bf16 v[14:17], v[106:109], v[184:187], v[14:17]
	v_mfma_f32_16x16x32_bf16 v[10:13], v[220:223], v[184:187], v[10:13]
	v_mfma_f32_16x16x32_bf16 v[6:9], v[110:113], v[204:207], v[6:9]
	v_mfma_f32_16x16x32_bf16 v[2:5], v[224:227], v[204:207], v[2:5]
	v_mfma_f32_16x16x32_bf16 v[134:137], v[110:113], v[78:81], v[30:33]
	v_mfma_f32_16x16x32_bf16 v[142:145], v[224:227], v[78:81], v[26:29]
	v_mfma_f32_16x16x32_bf16 v[146:149], v[110:113], v[188:191], v[14:17]
	v_mfma_f32_16x16x32_bf16 v[150:153], v[224:227], v[188:191], v[10:13]
	s_setprio 0
	s_barrier
	s_nop 0
	ds_read_b128 v[10:13], v173
	ds_read_b128 v[14:17], v173 offset:1024
	ds_read_b128 v[184:187], v173 offset:2048
	ds_read_b128 v[188:191], v173 offset:3072
	ds_read_b128 v[26:29], v168 offset:32768
	ds_read_b128 v[30:33], v168 offset:33792
	ds_read_b128 v[42:45], v169 offset:32768
	ds_read_b128 v[46:49], v169 offset:33792
	ds_read_b128 v[200:203], v170 offset:32768
	ds_read_b128 v[204:207], v170 offset:33792
	ds_read_b128 v[220:223], v171 offset:32768
	ds_read_b128 v[224:227], v171 offset:33792
	s_waitcnt vmcnt(2)
	s_barrier
; #define LDA(dst, b, h) for (int m = 0; m < 4; ++m) for (int k = 0; k < 2; ++k) \
;     dst[m][k] = *reinterpret_cast<const bf16x8*>((char*)SA(b, h) + lds_byte(wr * 64 + m * 16 + fr, k * 32 + fq * 8))
; #define LDB(dst, b, h) for (int n = 0; n < 2; ++n) for (int k = 0; k < 2; ++k) \
;     dst[n][k] = *reinterpret_cast<const bf16x8*>((char*)SB(b, h) + lds_byte(wc * 32 + n * 16 + fr, k * 32 + fq * 8))
; #define MMA(ai, bj, At, Bt_) do { __builtin_amdgcn_s_setprio(1); \
;     for (int m = 0; m < 4; ++m) for (int n = 0; n < 2; ++n) for (int k = 0; k < 2; ++k) \
;       acc[ai][bj][m][n] = __builtin_amdgcn_mfma_f32_16x16x32_bf16(Bt_[n][k], At[m][k], acc[ai][bj][m][n], 0, 0, 0); \
;     __builtin_amdgcn_s_setprio(0); } while (0)
; #define WAIT_V(n) asm volatile("s_waitcnt vmcnt(" #n ")" ::: "memory")
; #define WAIT_L(n) asm volatile("s_waitcnt lgkmcnt(" #n ")" ::: "memory")
; #define BAR __builtin_amdgcn_s_barrier()
; template <int EPI> ...
;     ...
;       LDA(At, 0, 1); WAIT_V(4); BAR; WAIT_L(0); MMA(1, 0, At, B0); MMA(1, 1, At, B1); BAR; }
;     { LDB(B0, 1, 0); LDA(At, 1, 0); WAIT_V(2); BAR; WAIT_L(0); MMA(0, 0, At, B0); BAR;
;       LDB(B1, 1, 1); WAIT_V(0); BAR; WAIT_L(0); MMA(0, 1, At, B1); BAR;
;       LDA(At, 1, 1); BAR; WAIT_L(0); MMA(1, 0, At, B0); MMA(1, 1, At, B1); BAR; }
;     if (wr == 0) BAR;
	s_waitcnt lgkmcnt(0)
	s_setprio 1
	s_waitcnt lgkmcnt(0)
	v_mfma_f32_16x16x32_bf16 v[74:77], v[10:13], v[26:29], v[126:129]
	v_mfma_f32_16x16x32_bf16 v[126:129], v[14:17], v[30:33], v[74:77]
	v_mfma_f32_16x16x32_bf16 v[74:77], v[184:187], v[26:29], v[122:125]
	v_mfma_f32_16x16x32_bf16 v[122:125], v[188:191], v[30:33], v[74:77]
	v_mfma_f32_16x16x32_bf16 v[74:77], v[10:13], v[42:45], v[118:121]
	v_mfma_f32_16x16x32_bf16 v[110:113], v[14:17], v[46:49], v[74:77]
	v_mfma_f32_16x16x32_bf16 v[74:77], v[184:187], v[42:45], v[114:117]
	v_mfma_f32_16x16x32_bf16 v[106:109], v[188:191], v[46:49], v[74:77]
	v_mfma_f32_16x16x32_bf16 v[74:77], v[10:13], v[200:203], v[212:215]
	v_mfma_f32_16x16x32_bf16 v[94:97], v[14:17], v[204:207], v[74:77]
	v_mfma_f32_16x16x32_bf16 v[74:77], v[184:187], v[200:203], v[216:219]
	v_mfma_f32_16x16x32_bf16 v[90:93], v[188:191], v[204:207], v[74:77]
	v_mfma_f32_16x16x32_bf16 v[74:77], v[10:13], v[220:223], v[102:105]
	v_mfma_f32_16x16x32_bf16 v[78:81], v[14:17], v[224:227], v[74:77]
	v_mfma_f32_16x16x32_bf16 v[74:77], v[184:187], v[220:223], v[98:101]
	v_mfma_f32_16x16x32_bf16 v[74:77], v[188:191], v[224:227], v[74:77]
	s_setprio 0
	s_barrier
	ds_read_b128 v[212:215], v174
	ds_read_b128 v[216:219], v174 offset:1024
	ds_read_b128 v[236:239], v174 offset:2048
	ds_read_b128 v[240:243], v174 offset:3072
	s_waitcnt vmcnt(0)
	s_barrier
	s_waitcnt lgkmcnt(0)
	s_setprio 1
	s_waitcnt lgkmcnt(0)
	v_mfma_f32_16x16x32_bf16 v[98:101], v[212:215], v[26:29], v[228:231]
	v_mfma_f32_16x16x32_bf16 v[26:29], v[236:239], v[26:29], v[156:159]
	v_mfma_f32_16x16x32_bf16 v[114:117], v[240:243], v[30:33], v[26:29]
	v_mfma_f32_16x16x32_bf16 v[26:29], v[212:215], v[42:45], v[86:89]
	v_mfma_f32_16x16x32_bf16 v[102:105], v[216:219], v[46:49], v[26:29]
	v_mfma_f32_16x16x32_bf16 v[26:29], v[236:239], v[42:45], v[82:85]
	v_mfma_f32_16x16x32_bf16 v[118:121], v[216:219], v[30:33], v[98:101]
	v_mfma_f32_16x16x32_bf16 v[98:101], v[240:243], v[46:49], v[26:29]
	v_mfma_f32_16x16x32_bf16 v[26:29], v[212:215], v[200:203], v[176:179]
	v_mfma_f32_16x16x32_bf16 v[86:89], v[216:219], v[204:207], v[26:29]
	v_mfma_f32_16x16x32_bf16 v[26:29], v[236:239], v[200:203], v[180:183]
	v_mfma_f32_16x16x32_bf16 v[82:85], v[240:243], v[204:207], v[26:29]
	v_mfma_f32_16x16x32_bf16 v[26:29], v[212:215], v[220:223], v[70:73]
	v_mfma_f32_16x16x32_bf16 v[70:73], v[216:219], v[224:227], v[26:29]
	v_mfma_f32_16x16x32_bf16 v[26:29], v[236:239], v[220:223], v[66:69]
	v_mfma_f32_16x16x32_bf16 v[66:69], v[240:243], v[224:227], v[26:29]
	s_setprio 0
	s_barrier
	ds_read_b128 v[154:157], v168 offset:49152
	ds_read_b128 v[176:179], v168 offset:50176
	ds_read_b128 v[180:183], v169 offset:49152
	ds_read_b128 v[200:203], v169 offset:50176
	ds_read_b128 v[204:207], v170 offset:49152
	ds_read_b128 v[220:223], v170 offset:50176
	ds_read_b128 v[224:227], v171 offset:49152
	ds_read_b128 v[228:231], v171 offset:50176
	s_barrier
	s_waitcnt lgkmcnt(0)
	s_setprio 1
	s_waitcnt lgkmcnt(0)
	v_mfma_f32_16x16x32_bf16 v[26:29], v[10:13], v[154:157], v[62:65]
	v_mfma_f32_16x16x32_bf16 v[62:65], v[14:17], v[176:179], v[26:29]
	v_mfma_f32_16x16x32_bf16 v[26:29], v[184:187], v[154:157], v[58:61]
	v_mfma_f32_16x16x32_bf16 v[58:61], v[188:191], v[176:179], v[26:29]
	v_mfma_f32_16x16x32_bf16 v[26:29], v[10:13], v[180:183], v[54:57]
	v_mfma_f32_16x16x32_bf16 v[46:49], v[14:17], v[200:203], v[26:29]
	v_mfma_f32_16x16x32_bf16 v[26:29], v[184:187], v[180:183], v[50:53]
	v_mfma_f32_16x16x32_bf16 v[42:45], v[188:191], v[200:203], v[26:29]
	v_mfma_f32_16x16x32_bf16 v[26:29], v[10:13], v[204:207], v[208:211]
	v_mfma_f32_16x16x32_bf16 v[10:13], v[10:13], v[224:227], v[38:41]
	v_mfma_f32_16x16x32_bf16 v[30:33], v[14:17], v[220:223], v[26:29]
	v_mfma_f32_16x16x32_bf16 v[26:29], v[184:187], v[204:207], v[232:235]
	v_mfma_f32_16x16x32_bf16 v[14:17], v[14:17], v[228:231], v[10:13]
	v_mfma_f32_16x16x32_bf16 v[10:13], v[184:187], v[224:227], v[34:37]
	v_mfma_f32_16x16x32_bf16 v[26:29], v[188:191], v[220:223], v[26:29]
	v_mfma_f32_16x16x32_bf16 v[10:13], v[188:191], v[228:231], v[10:13]
	s_setprio 0
	s_setprio 1
	v_mfma_f32_16x16x32_bf16 v[34:37], v[212:215], v[154:157], v[134:137]
	v_mfma_f32_16x16x32_bf16 v[54:57], v[216:219], v[176:179], v[34:37]
	v_mfma_f32_16x16x32_bf16 v[34:37], v[236:239], v[154:157], v[142:145]
	v_mfma_f32_16x16x32_bf16 v[18:21], v[236:239], v[180:183], v[18:21]
	v_mfma_f32_16x16x32_bf16 v[50:53], v[240:243], v[176:179], v[34:37]
	v_mfma_f32_16x16x32_bf16 v[22:25], v[212:215], v[180:183], v[22:25]
	v_mfma_f32_16x16x32_bf16 v[34:37], v[240:243], v[200:203], v[18:21]
	v_mfma_f32_16x16x32_bf16 v[18:21], v[212:215], v[204:207], v[146:149]
	v_mfma_f32_16x16x32_bf16 v[38:41], v[216:219], v[200:203], v[22:25]
	v_mfma_f32_16x16x32_bf16 v[22:25], v[216:219], v[220:223], v[18:21]
	v_mfma_f32_16x16x32_bf16 v[18:21], v[236:239], v[204:207], v[150:153]
	v_mfma_f32_16x16x32_bf16 v[6:9], v[212:215], v[224:227], v[6:9]
	v_mfma_f32_16x16x32_bf16 v[2:5], v[236:239], v[224:227], v[2:5]
	v_mfma_f32_16x16x32_bf16 v[18:21], v[240:243], v[220:223], v[18:21]
	v_mfma_f32_16x16x32_bf16 v[6:9], v[216:219], v[228:231], v[6:9]
	v_mfma_f32_16x16x32_bf16 v[2:5], v[240:243], v[228:231], v[2:5]
	s_setprio 0
	s_barrier
	s_and_saveexec_b64 s[14:15], s[6:7]
	s_cbranch_execz .LBB0_544
	s_barrier
